# plus: final-phase ssq prefetch one row ahead; prologue-phase row loads batched with counted waits
# speedup vs baseline: 1.0013x; 1.0013x over previous
.LBB0_8:
	v_lshl_add_u64 v[44:45], s[4:5], 0, v[18:19]
	s_waitcnt lgkmcnt(0)
	global_load_dwordx4 v[32:35], v[44:45], off nt
	global_load_dwordx4 v[52:55], v[44:45], off offset:1024 nt
	global_load_dwordx4 v[56:59], v[44:45], off offset:2048 nt
	global_load_dwordx4 v[60:63], v[44:45], off offset:3072 nt
	v_lshl_add_u64 v[48:49], s[16:17], 0, v[18:19]
	s_waitcnt vmcnt(3)
	v_pk_mul_f32 v[36:37], v[4:5], v[34:35]
	v_pk_mul_f32 v[38:39], v[2:3], v[32:33]
	global_store_dwordx4 v[48:49], v[32:35], off nt
	v_cvt_pk_bf16_f32 v38, v38, v39
	v_cvt_pk_bf16_f32 v39, v36, v37
	global_store_dwordx2 v[22:23], v[38:39], off offset:-1024
	v_mul_f32_e32 v31, v33, v33
	v_mul_f32_e32 v33, v35, v35
	v_fmac_f32_e32 v31, v32, v32
	v_fmac_f32_e32 v33, v34, v34
	v_add_f32_e32 v31, v31, v33
	s_waitcnt vmcnt(4)
	v_pk_mul_f32 v[40:41], v[8:9], v[54:55]
	v_pk_mul_f32 v[42:43], v[6:7], v[52:53]
	global_store_dwordx4 v[48:49], v[52:55], off offset:1024 nt
	v_cvt_pk_bf16_f32 v42, v42, v43
	v_cvt_pk_bf16_f32 v43, v40, v41
	global_store_dwordx2 v[22:23], v[42:43], off offset:-512
	v_mul_f32_e32 v32, v53, v53
	v_mul_f32_e32 v33, v55, v55
	v_fmac_f32_e32 v32, v52, v52
	v_fmac_f32_e32 v33, v54, v54
	v_add_f32_e32 v32, v32, v33
	v_add_f32_e32 v31, v31, v32
	s_waitcnt vmcnt(5)
	v_pk_mul_f32 v[46:47], v[12:13], v[58:59]
	v_pk_mul_f32 v[50:51], v[10:11], v[56:57]
	global_store_dwordx4 v[48:49], v[56:59], off offset:2048 nt
	v_cvt_pk_bf16_f32 v50, v50, v51
	v_cvt_pk_bf16_f32 v51, v46, v47
	global_store_dwordx2 v[22:23], v[50:51], off
	v_mul_f32_e32 v32, v57, v57
	v_mul_f32_e32 v33, v59, v59
	v_fmac_f32_e32 v32, v56, v56
	v_fmac_f32_e32 v33, v58, v58
	v_add_f32_e32 v32, v32, v33
	v_add_f32_e32 v31, v31, v32
	s_waitcnt vmcnt(6)
	v_mul_f32_e32 v32, v61, v61
	v_mul_f32_e32 v33, v63, v63
	v_fmac_f32_e32 v32, v60, v60
	v_fmac_f32_e32 v33, v62, v62
	v_add_f32_e32 v32, v32, v33
	v_add_f32_e32 v31, v31, v32
	ds_bpermute_b32 v32, v25, v31
	v_pk_mul_f32 v[34:35], v[16:17], v[62:63]
	v_pk_mul_f32 v[36:37], v[14:15], v[60:61]
	global_store_dwordx4 v[48:49], v[60:63], off offset:3072 nt
	v_cvt_pk_bf16_f32 v36, v36, v37
	s_waitcnt lgkmcnt(0)
	v_add_f32_e32 v31, v31, v32
	ds_bpermute_b32 v32, v26, v31
	v_cvt_pk_bf16_f32 v37, v34, v35
	global_store_dwordx2 v[22:23], v[36:37], off offset:512
	s_waitcnt lgkmcnt(0)
	v_add_f32_e32 v31, v31, v32
	ds_bpermute_b32 v32, v27, v31
	s_waitcnt lgkmcnt(0)
	v_add_f32_e32 v31, v31, v32
	ds_bpermute_b32 v32, v28, v31
	s_waitcnt lgkmcnt(0)
	v_add_f32_e32 v31, v31, v32
	ds_bpermute_b32 v32, v29, v31
	s_waitcnt lgkmcnt(0)
	v_add_f32_e32 v31, v31, v32
	ds_bpermute_b32 v32, v30, v31
	s_and_saveexec_b64 s[18:19], vcc
	s_cbranch_execz .LBB0_7
	s_waitcnt lgkmcnt(0)
	v_add_f32_e32 v31, v31, v32
	v_cndmask_b32_e64 v31, 0, v31, s[0:1]
	global_store_dword v[20:21], v31, off
	s_branch .LBB0_7

.Lfin_loop:
	global_load_dwordx4 v[28:31], v[18:19], off offset:-3072 nt
	global_load_dwordx4 v[32:35], v[18:19], off offset:-2048 nt
	global_load_dwordx4 v[36:39], v[18:19], off offset:-1024 nt
	global_load_dwordx4 v[40:43], v[18:19], off nt
	s_waitcnt vmcnt(4)
	ds_bpermute_b32 v44, v20, v27
	s_add_i32 s8, s8, s2
	v_lshl_add_u64 v[16:17], v[16:17], 0, s[6:7]
	v_mov_b32_e32 v46, 0
	s_and_saveexec_b64 s[12:13], vcc
	global_load_dword v46, v[16:17], off
	s_or_b64 exec, exec, s[12:13]
	s_cmp_lt_i32 s8, 0x8000
	s_waitcnt lgkmcnt(0)
	v_add_f32_e32 v27, v27, v44
	ds_bpermute_b32 v44, v21, v27
	s_waitcnt lgkmcnt(0)
	v_add_f32_e32 v27, v27, v44
	ds_bpermute_b32 v44, v22, v27
	s_waitcnt lgkmcnt(0)
	v_add_f32_e32 v27, v27, v44
	ds_bpermute_b32 v44, v23, v27
	s_waitcnt lgkmcnt(0)
	v_add_f32_e32 v27, v27, v44
	ds_bpermute_b32 v44, v24, v27
	s_waitcnt lgkmcnt(0)
	v_add_f32_e32 v27, v27, v44
	ds_bpermute_b32 v44, v25, v27
	s_waitcnt lgkmcnt(0)
	v_add_f32_e32 v27, v27, v44
	v_fmamk_f32 v27, v27, 0x3a800000, v26
	v_mul_f32_e32 v44, 0x4b800000, v27
	v_cmp_gt_f32_e64 s[0:1], s3, v27
	s_waitcnt vmcnt(4)
	v_pk_mul_f32 v[30:31], v[2:3], v[30:31]
	v_cndmask_b32_e64 v27, v27, v44, s[0:1]
	v_rsq_f32_e32 v27, v27
	v_pk_mul_f32 v[28:29], v[0:1], v[28:29]
	s_waitcnt vmcnt(3)
	v_pk_mul_f32 v[34:35], v[6:7], v[34:35]
	v_pk_mul_f32 v[32:33], v[4:5], v[32:33]
	v_mul_f32_e32 v44, 0x45800000, v27
	v_cndmask_b32_e64 v44, v27, v44, s[0:1]
	s_waitcnt vmcnt(2)
	v_pk_mul_f32 v[38:39], v[10:11], v[38:39]
	v_pk_mul_f32 v[36:37], v[8:9], v[36:37]
	s_waitcnt vmcnt(1)
	v_pk_mul_f32 v[42:43], v[14:15], v[42:43]
	v_pk_mul_f32 v[40:41], v[12:13], v[40:41]
	v_pk_mul_f32 v[30:31], v[30:31], v[44:45] op_sel_hi:[1,0]
	v_pk_mul_f32 v[28:29], v[28:29], v[44:45] op_sel_hi:[1,0]
	v_pk_mul_f32 v[34:35], v[34:35], v[44:45] op_sel_hi:[1,0]
	v_pk_mul_f32 v[32:33], v[32:33], v[44:45] op_sel_hi:[1,0]
	v_pk_mul_f32 v[38:39], v[38:39], v[44:45] op_sel_hi:[1,0]
	v_pk_mul_f32 v[36:37], v[36:37], v[44:45] op_sel_hi:[1,0]
	v_pk_mul_f32 v[42:43], v[42:43], v[44:45] op_sel_hi:[1,0]
	v_pk_mul_f32 v[40:41], v[40:41], v[44:45] op_sel_hi:[1,0]
	global_store_dwordx4 v[18:19], v[28:31], off offset:-3072 nt
	global_store_dwordx4 v[18:19], v[32:35], off offset:-2048 nt
	global_store_dwordx4 v[18:19], v[36:39], off offset:-1024 nt
	global_store_dwordx4 v[18:19], v[40:43], off nt
	v_lshl_add_u64 v[18:19], v[18:19], 0, s[4:5]
	s_waitcnt vmcnt(4)
	v_mov_b32_e32 v27, v46
	s_cbranch_scc0 .LBB0_1983
	s_branch .Lfin_loop
